# v78 plus: barrier leaders do not wait for the acknowledgement of the generation-flag atomics
# baseline (speedup 1.0000x reference)
; __device__ __forceinline__ unsigned xb_ld(unsigned* p)              { return __hip_atomic_load(p, __ATOMIC_RELAXED, __HIP_MEMORY_SCOPE_AGENT); }
; #define XB_SPIN(cond, bar) do { unsigned _sp = 0; while (cond) { __builtin_amdgcn_s_sleep(1); \
;     if ((++_sp & 255u) == 0u) { if (xb_ld(&(bar)[XB_TMO])) break; if (_sp > XB_SPIN_CAP) { atomicAdd(&(bar)[XB_TMO], 1u); break; } } } } while (0)
; __device__ __forceinline__ void phase1(const Args& a, LAS unsigned char* L) {
;     ...
;     for (int r = bid; r < 48; r += G)
;         for (int c = tid; c < DM; c += 512) { float s = bada[2048 + c];
; #pragma unroll
;             for (int q = 0; q < 4; ++q) s += modp[(size_t)(q * 48 + r) * 3072 + 2048 + c];
;             gatef[r * DM + c] = s; }
; __device__ __forceinline__ void xcd_barrier(const XcdBarrier& b) {
;     ...
;             asm volatile("s_waitcnt vmcnt(0)" ::: "memory");
;         } else {
;             XB_SPIN(xb_ld(&bar[XB_XGEN(b.x)]) == gen, bar);
;             __builtin_amdgcn_fence(__ATOMIC_ACQUIRE, "agent");
;             asm volatile("s_waitcnt vmcnt(0)" ::: "memory");
;         }
;     }
;     __syncthreads();
.LBB0_100:
	s_or_b64 exec, exec, s[8:9]
.LBB0_101:
	s_or_b64 exec, exec, s[0:1]
	s_add_u32 s22, s28, 0x1e400000
	s_waitcnt lgkmcnt(0)
	v_mov_b32_e32 v0, v180
	s_addc_u32 s23, s29, 0
	s_barrier
	s_cmp_lt_i32 s2, 0xf9
	v_readfirstlane_b32 s12, v0
	s_cbranch_scc1 .LBB0_107
	s_mov_b32 s98, s2
	s_mov_b32 s99, s30
	s_sub_i32 s2, s2, 0xf9
	s_mov_b32 s30, 7
	v_ashrrev_i32_e32 v1, 31, v0
	s_movk_i32 s0, 0x400
	v_lshlrev_b64 v[8:9], 2, v[0:1]
	v_cmp_gt_i32_e32 vcc, s0, v0
	v_lshl_add_u64 v[4:5], s[54:55], 0, v[8:9]
	s_mov_b64 s[0:1], 0x2000
	s_lshl_b32 s13, s30, 10
	v_lshl_add_u64 v[4:5], v[4:5], 0, s[0:1]
	s_mul_i32 s0, s2, 0x3000
	s_mul_hi_i32 s1, s2, 0x3000
	s_add_u32 s0, s28, s0
	s_addc_u32 s1, s29, s1
	v_lshl_add_u64 v[6:7], s[0:1], 0, v[8:9]
	s_mov_b64 s[0:1], 0x1e102000
	v_lshl_add_u64 v[8:9], s[28:29], 0, v[8:9]
	v_add_u32_e32 v18, 0xfffffe00, v0
	v_lshl_add_u32 v2, s2, 10, v0
	v_lshl_add_u64 v[6:7], v[6:7], 0, s[0:1]
	s_mul_hi_i32 s5, s30, 0x3000
	s_mul_i32 s4, s30, 0x3000
	v_lshl_add_u64 v[8:9], v[8:9], 0, s[0:1]
	s_add_i32 s14, s2, 48
	s_add_i32 s15, s2, 0x60
	s_add_i32 s16, s2, 0x90
	s_movk_i32 s17, 0x1ff
	v_mov_b32_e32 v1, 0x3000
	s_mov_b32 s33, s2
	s_branch .LBB0_104

; #define OPAQUE_TID() int tid = threadIdx.x; asm volatile("" : "+v"(tid)); const int lane = tid & 63, wave = __builtin_amdgcn_readfirstlane(tid >> 6); (void)lane; (void)wave
; #define YM_LOAD(row) do { const bf16_t* ur_ = U + (size_t)(row) * LDU + cbase; _Pragma("unroll") for (int hp = 0; hp < 2; ++hp) { \
;         nh[hp] = *(const u32x4*)(ur_ + C_V + 512 * hp); nz[hp] = *(const u32x4*)(ur_ + C_ZM + 512 * hp); } } while (0)
; __device__ __forceinline__ unsigned xb_ld(unsigned* p)              { return __hip_atomic_load(p, __ATOMIC_RELAXED, __HIP_MEMORY_SCOPE_AGENT); }
; #define XB_SPIN(cond, bar) do { unsigned _sp = 0; while (cond) { __builtin_amdgcn_s_sleep(1); \
;     if ((++_sp & 255u) == 0u) { if (xb_ld(&(bar)[XB_TMO])) break; if (_sp > XB_SPIN_CAP) { atomicAdd(&(bar)[XB_TMO], 1u); break; } } } } while (0)
; __device__ __forceinline__ void ym_finalize(const Args& a, bool dry = false) {
;     OPAQUE_TID();
;     bf16_t* U = (bf16_t*)(a.ws + WS_U);
;     const int gw = blockIdx.x * 8 + wave, NGW = gridDim.x * 8;
;     const int cbase = (lane >> 5) * 256 + 8 * (lane & 31);
;     f32x4 gh[2][2];
; #pragma unroll
;     for (int hp = 0; hp < 2; ++hp) { gh[hp][0] = *(const f32x4*)(a.in[16] + cbase + 512 * hp); gh[hp][1] = *(const f32x4*)(a.in[16] + cbase + 512 * hp + 4); }
;     u32x4 nh[2], nz[2];
;     ...
;     if (gw < MT) YM_LOAD(gw);
;     for (int row = gw; row < MT; row += NGW) {
;         u32x4 ch[2], cz[2];
; #pragma unroll
;         for (int hp = 0; hp < 2; ++hp) { ch[hp] = nh[hp]; cz[hp] = nz[hp]; }
;         if (row + NGW < MT) YM_LOAD(row + NGW);
; __device__ __forceinline__ void xcd_barrier(const XcdBarrier& b) {
;     ...
;             asm volatile("s_waitcnt vmcnt(0)" ::: "memory");
;         } else {
;             XB_SPIN(xb_ld(&bar[XB_XGEN(b.x)]) == gen, bar);
;             __builtin_amdgcn_fence(__ATOMIC_ACQUIRE, "agent");
;             asm volatile("s_waitcnt vmcnt(0)" ::: "memory");
;         }
;     }
;     __syncthreads();
.LBB0_1127:
	s_or_b64 exec, exec, s[8:9]
.LBB0_1128:
	s_or_b64 exec, exec, s[0:1]
	s_bitcmp0_b32 s2, 3
	s_cselect_b64 s[4:5], -1, 0
	s_and_b64 vcc, exec, s[4:5]
	s_waitcnt lgkmcnt(0)
	s_barrier
	s_cbranch_vccnz .LBB0_1134
	v_mov_b32_e32 v20, v180
	s_lshr_b32 s98, s2, 4
	s_sub_i32 s98, s2, s98
	s_add_i32 s98, s98, -1
	s_lshl_b32 s1, s98, 3
	s_movk_i32 s99, 0x780
	v_readfirstlane_b32 s0, v20
	s_ashr_i32 s0, s0, 6
	s_add_i32 s10, s0, s1
	s_cmp_gt_i32 s10, 0x83ff
	s_cbranch_scc1 .LBB0_1134
	v_lshlrev_b32_e32 v0, 3, v20
	s_mul_i32 s0, s10, 0x3800
	v_and_b32_e32 v8, 0x1f8, v0
	s_mul_hi_i32 s1, s10, 0x3800
	s_add_u32 s0, s28, s0
	s_addc_u32 s1, s29, s1
	v_lshlrev_b32_e32 v48, 1, v8
	v_mov_b32_e32 v49, 0
	v_lshlrev_b32_e32 v21, 2, v8
	v_lshl_add_u64 v[8:9], s[0:1], 0, v[48:49]
	s_movk_i32 s6, 0x3000
	v_add_co_u32_e32 v22, vcc, s6, v8
	s_movk_i32 s11, 0x1000
	s_nop 0
	v_addc_co_u32_e32 v23, vcc, 0, v9, vcc
	v_add_co_u32_e32 v24, vcc, s11, v8
	global_load_dwordx4 v[0:3], v21, s[20:21] offset:2048
	global_load_dwordx4 v[4:7], v21, s[20:21] offset:2064
	v_addc_co_u32_e32 v25, vcc, 0, v9, vcc
	global_load_dwordx4 v[36:39], v[24:25], off
	global_load_dwordx4 v[16:19], v[24:25], off offset:1024
	global_load_dwordx4 v[44:47], v[22:23], off
	global_load_dwordx4 v[40:43], v[22:23], off offset:1024
	global_load_dwordx4 v[8:11], v21, s[20:21]
	global_load_dwordx4 v[12:15], v21, s[20:21] offset:16
	v_mbcnt_hi_u32_b32 v21, -1, v181
	v_and_b32_e32 v22, 64, v21
	v_xor_b32_e32 v23, 1, v21
	v_add_u32_e32 v22, 64, v22
	v_xor_b32_e32 v24, 2, v21
	v_cmp_lt_i32_e32 vcc, v23, v22
	v_xor_b32_e32 v25, 4, v21
	v_xor_b32_e32 v26, 8, v21
	v_cndmask_b32_e32 v23, v21, v23, vcc
	v_cmp_lt_i32_e32 vcc, v24, v22
	v_xor_b32_e32 v27, 16, v21
	s_add_i32 s6, s10, s99
	v_cndmask_b32_e32 v24, v21, v24, vcc
	v_cmp_lt_i32_e32 vcc, v25, v22
	v_and_b32_e32 v20, 63, v20
	s_mul_hi_i32 s7, s6, 0x3800
	v_cndmask_b32_e32 v25, v21, v25, vcc
	v_cmp_lt_i32_e32 vcc, v26, v22
	s_mulk_i32 s6, 0x3800
	v_lshlrev_b32_e32 v48, 4, v20
	v_cndmask_b32_e32 v26, v21, v26, vcc
	v_cmp_lt_i32_e32 vcc, v27, v22
	v_lshlrev_b32_e32 v51, 2, v23
	v_lshlrev_b32_e32 v52, 2, v24
	v_cndmask_b32_e32 v21, v21, v27, vcc
	v_lshlrev_b32_e32 v53, 2, v25
	v_lshlrev_b32_e32 v54, 2, v26
	v_lshlrev_b32_e32 v55, 2, v21
	s_add_u32 s6, s28, s6
	s_mul_hi_i32 s12, s99, 0x3800
	s_mul_i32 s13, s99, 0x3800
	v_mov_b32_e32 v50, 0x358637bd
	s_mov_b32 s14, 0x800000
	s_addc_u32 s7, s29, s7
	s_waitcnt vmcnt(5)
	v_mov_b64_e32 v[28:29], v[36:37]
	s_waitcnt vmcnt(4)
	v_mov_b64_e32 v[26:27], v[18:19]
	s_waitcnt vmcnt(3)
	v_mov_b64_e32 v[20:21], v[44:45]
	s_waitcnt vmcnt(2)
	v_mov_b64_e32 v[32:33], v[40:41]
	v_mov_b64_e32 v[24:25], v[16:17]
	v_mov_b64_e32 v[30:31], v[38:39]
	v_mov_b64_e32 v[22:23], v[46:47]
	v_mov_b64_e32 v[34:35], v[42:43]
	s_branch .LBB0_1132
